# P7b (gated merge) epilogue with its GA/GB tile loads six deep in flight instead of one at a time; on top of v162
# speedup vs baseline: 1.0048x; 1.0017x over previous
; __device__ __forceinline__ float bf_lo(unsigned w) { return __uint_as_float(w << 16); }
; __device__ __forceinline__ float bf_hi(unsigned w) { return __uint_as_float(w & 0xffff0000u); }
; __device__ __forceinline__ u32x4 pack8(f32x4 a, f32x4 b) { u32x4 w; w.x = cvt_pk_bf16(a[0], a[1]); w.y = cvt_pk_bf16(a[2], a[3]); w.z = cvt_pk_bf16(b[0], b[1]); w.w = cvt_pk_bf16(b[2], b[3]); return w; }
;     __device__ __forceinline__ void operator()(const Acc& acc, const Unit& u, int wr, int wc, int fr, int fq) const {
;     ...
;         for (int ai = 0; ai < 2; ++ai)
; #pragma unroll
;             for (int m = 0; m < 4; ++m) { const size_t ro = (size_t)(row0 + ai * HALF + m * 16) * DM + col0;
; #pragma unroll
;                 for (int bj = 0; bj < 2; ++bj) {
;                     const u32x4 ga = *(const u32x4*)(GA + ro + bj * HALF);
;                     const f32x4 a0 = acc[ai][bj][m][0], a1 = acc[ai][bj][m][1];
;                     f32x4 r0, r1;
;                     if (MODE == 0) {
;                         r0[0] = bf_lo(ga.x) * a0[0]; r0[1] = bf_hi(ga.x) * a0[1]; r0[2] = bf_lo(ga.y) * a0[2]; r0[3] = bf_hi(ga.y) * a0[3];
;                         r1[0] = bf_lo(ga.z) * a1[0]; r1[1] = bf_hi(ga.z) * a1[1]; r1[2] = bf_lo(ga.w) * a1[2]; r1[3] = bf_hi(ga.w) * a1[3];
;                         *(u32x4*)(GA + ro + bj * HALF) = pack8(r0, r1);
;                     } else {
;                         const u32x4 gb = __builtin_nontemporal_load((const u32x4*)(GB + ro + bj * HALF));
;                         r0[0] = bf_lo(ga.x) + bf_lo(gb.x) * a0[0]; r0[1] = bf_hi(ga.x) + bf_hi(gb.x) * a0[1]; r0[2] = bf_lo(ga.y) + bf_lo(gb.y) * a0[2]; r0[3] = bf_hi(ga.y) + bf_hi(gb.y) * a0[3];
;                         r1[0] = bf_lo(ga.z) + bf_lo(gb.z) * a1[0]; r1[1] = bf_hi(ga.z) + bf_hi(gb.z) * a1[1]; r1[2] = bf_lo(ga.w) + bf_lo(gb.w) * a1[2]; r1[3] = bf_hi(ga.w) + bf_hi(gb.w) * a1[3];
;                         *(u32x4*)(GB + ro + bj * HALF) = pack8(r0, r1);
.LBB0_1040:
	v_lshl_add_u32 v148, s68, 8, v150
	v_lshl_or_b32 v146, s42, 8, v152
	v_lshl_add_u32 v144, v148, 10, v146
	v_lshlrev_b32_e32 v144, 1, v144
	s_andn2_b64 vcc, exec, s[4:5]
	s_mov_b64 s[4:5], -1
	v_mov_b32_e32 v145, v144
	global_load_dwordx4 v[176:179], v145, s[8:9]
	global_load_dwordx4 v[180:183], v145, s[28:29] nt
	global_load_dwordx4 v[184:187], v145, s[8:9] offset:256
	global_load_dwordx4 v[188:191], v145, s[28:29] offset:256 nt
	v_add_u32_e32 v145, 0x8000, v144
	global_load_dwordx4 v[192:195], v145, s[8:9]
	global_load_dwordx4 v[196:199], v145, s[28:29] nt
	global_load_dwordx4 v[200:203], v145, s[8:9] offset:256
	global_load_dwordx4 v[204:207], v145, s[28:29] offset:256 nt
	v_add_u32_e32 v145, 0x10000, v144
	global_load_dwordx4 v[208:211], v145, s[8:9]
	global_load_dwordx4 v[212:215], v145, s[28:29] nt
	global_load_dwordx4 v[216:219], v145, s[8:9] offset:256
	global_load_dwordx4 v[220:223], v145, s[28:29] offset:256 nt
	s_waitcnt vmcnt(10)
	v_lshlrev_b32_e32 v156, 16, v176
	v_lshlrev_b32_e32 v168, 16, v180
	v_lshlrev_b32_e32 v157, 16, v177
	v_lshlrev_b32_e32 v169, 16, v181
	v_lshlrev_b32_e32 v158, 16, v178
	v_lshlrev_b32_e32 v170, 16, v182
	v_lshlrev_b32_e32 v159, 16, v179
	v_lshlrev_b32_e32 v171, 16, v183
	v_and_b32_e32 v176, 0xffff0000, v176
	v_and_b32_e32 v180, 0xffff0000, v180
	v_and_b32_e32 v177, 0xffff0000, v177
	v_and_b32_e32 v181, 0xffff0000, v181
	v_and_b32_e32 v178, 0xffff0000, v178
	v_and_b32_e32 v182, 0xffff0000, v182
	v_and_b32_e32 v179, 0xffff0000, v179
	v_and_b32_e32 v183, 0xffff0000, v183
	v_fma_f32 v124, v124, v168, v156
	v_fma_f32 v125, v125, v180, v176
	v_fma_f32 v126, v126, v169, v157
	v_fma_f32 v127, v127, v181, v177
	v_fma_f32 v120, v120, v170, v158
	v_fma_f32 v121, v121, v182, v178
	v_fma_f32 v122, v122, v171, v159
	v_fma_f32 v123, v123, v183, v179
	v_cvt_pk_bf16_f32 v124, v124, v125
	v_cvt_pk_bf16_f32 v125, v126, v127
	v_cvt_pk_bf16_f32 v126, v120, v121
	v_cvt_pk_bf16_f32 v127, v122, v123
	v_mov_b32_e32 v146, v144
	global_store_dwordx4 v146, v[124:127], s[28:29]
	v_add_u32_e32 v145, 0x18000, v144
	global_load_dwordx4 v[176:179], v145, s[8:9]
	global_load_dwordx4 v[180:183], v145, s[28:29] nt
	s_waitcnt vmcnt(11)
	v_lshlrev_b32_e32 v156, 16, v184
	v_lshlrev_b32_e32 v168, 16, v188
	v_lshlrev_b32_e32 v157, 16, v185
	v_lshlrev_b32_e32 v169, 16, v189
	v_lshlrev_b32_e32 v158, 16, v186
	v_lshlrev_b32_e32 v170, 16, v190
	v_lshlrev_b32_e32 v159, 16, v187
	v_lshlrev_b32_e32 v171, 16, v191
	v_and_b32_e32 v184, 0xffff0000, v184
	v_and_b32_e32 v188, 0xffff0000, v188
	v_and_b32_e32 v185, 0xffff0000, v185
	v_and_b32_e32 v189, 0xffff0000, v189
	v_and_b32_e32 v186, 0xffff0000, v186
	v_and_b32_e32 v190, 0xffff0000, v190
	v_and_b32_e32 v187, 0xffff0000, v187
	v_and_b32_e32 v191, 0xffff0000, v191
	v_fma_f32 v116, v116, v168, v156
	v_fma_f32 v117, v117, v188, v184
	v_fma_f32 v118, v118, v169, v157
	v_fma_f32 v119, v119, v189, v185
	v_fma_f32 v112, v112, v170, v158
	v_fma_f32 v113, v113, v190, v186
	v_fma_f32 v114, v114, v171, v159
	v_fma_f32 v115, v115, v191, v187
	v_cvt_pk_bf16_f32 v116, v116, v117
	v_cvt_pk_bf16_f32 v117, v118, v119
	v_cvt_pk_bf16_f32 v118, v112, v113
	v_cvt_pk_bf16_f32 v119, v114, v115
	global_store_dwordx4 v146, v[116:119], s[28:29] offset:256
	global_load_dwordx4 v[184:187], v145, s[8:9] offset:256
	global_load_dwordx4 v[188:191], v145, s[28:29] offset:256 nt
	s_waitcnt vmcnt(12)
	v_lshlrev_b32_e32 v156, 16, v192
	v_lshlrev_b32_e32 v168, 16, v196
	v_lshlrev_b32_e32 v157, 16, v193
	v_lshlrev_b32_e32 v169, 16, v197
	v_lshlrev_b32_e32 v158, 16, v194
	v_lshlrev_b32_e32 v170, 16, v198
	v_lshlrev_b32_e32 v159, 16, v195
	v_lshlrev_b32_e32 v171, 16, v199
	v_and_b32_e32 v192, 0xffff0000, v192
	v_and_b32_e32 v196, 0xffff0000, v196
	v_and_b32_e32 v193, 0xffff0000, v193
	v_and_b32_e32 v197, 0xffff0000, v197
	v_and_b32_e32 v194, 0xffff0000, v194
	v_and_b32_e32 v198, 0xffff0000, v198
	v_and_b32_e32 v195, 0xffff0000, v195
	v_and_b32_e32 v199, 0xffff0000, v199
	v_fma_f32 v108, v108, v168, v156
	v_fma_f32 v109, v109, v196, v192
	v_fma_f32 v110, v110, v169, v157
	v_fma_f32 v111, v111, v197, v193
	v_fma_f32 v104, v104, v170, v158
	v_fma_f32 v105, v105, v198, v194
	v_fma_f32 v106, v106, v171, v159
	v_fma_f32 v107, v107, v199, v195
	v_cvt_pk_bf16_f32 v108, v108, v109
	v_cvt_pk_bf16_f32 v109, v110, v111
	v_cvt_pk_bf16_f32 v110, v104, v105
	v_cvt_pk_bf16_f32 v111, v106, v107
	v_add_u32_e32 v146, 0x8000, v144
	global_store_dwordx4 v146, v[108:111], s[28:29]
	v_add_u32_e32 v145, 0x40000, v144
	global_load_dwordx4 v[192:195], v145, s[8:9]
	global_load_dwordx4 v[196:199], v145, s[28:29] nt
	s_waitcnt vmcnt(13)
	v_lshlrev_b32_e32 v156, 16, v200
	v_lshlrev_b32_e32 v168, 16, v204
	v_lshlrev_b32_e32 v157, 16, v201
	v_lshlrev_b32_e32 v169, 16, v205
	v_lshlrev_b32_e32 v158, 16, v202
	v_lshlrev_b32_e32 v170, 16, v206
	v_lshlrev_b32_e32 v159, 16, v203
	v_lshlrev_b32_e32 v171, 16, v207
	v_and_b32_e32 v200, 0xffff0000, v200
	v_and_b32_e32 v204, 0xffff0000, v204
	v_and_b32_e32 v201, 0xffff0000, v201
	v_and_b32_e32 v205, 0xffff0000, v205
	v_and_b32_e32 v202, 0xffff0000, v202
	v_and_b32_e32 v206, 0xffff0000, v206
	v_and_b32_e32 v203, 0xffff0000, v203
	v_and_b32_e32 v207, 0xffff0000, v207
	v_fma_f32 v100, v100, v168, v156
	v_fma_f32 v101, v101, v204, v200
	v_fma_f32 v102, v102, v169, v157
	v_fma_f32 v103, v103, v205, v201
	v_fma_f32 v96, v96, v170, v158
	v_fma_f32 v97, v97, v206, v202
	v_fma_f32 v98, v98, v171, v159
	v_fma_f32 v99, v99, v207, v203
	v_cvt_pk_bf16_f32 v100, v100, v101
	v_cvt_pk_bf16_f32 v101, v102, v103
	v_cvt_pk_bf16_f32 v102, v96, v97
	v_cvt_pk_bf16_f32 v103, v98, v99
	global_store_dwordx4 v146, v[100:103], s[28:29] offset:256
	global_load_dwordx4 v[200:203], v145, s[8:9] offset:256
	global_load_dwordx4 v[204:207], v145, s[28:29] offset:256 nt
	s_waitcnt vmcnt(14)
; __device__ __forceinline__ float bf_lo(unsigned w) { return __uint_as_float(w << 16); }
; __device__ __forceinline__ float bf_hi(unsigned w) { return __uint_as_float(w & 0xffff0000u); }
; __device__ __forceinline__ u32x4 pack8(f32x4 a, f32x4 b) { u32x4 w; w.x = cvt_pk_bf16(a[0], a[1]); w.y = cvt_pk_bf16(a[2], a[3]); w.z = cvt_pk_bf16(b[0], b[1]); w.w = cvt_pk_bf16(b[2], b[3]); return w; }
;     __device__ __forceinline__ void operator()(const Acc& acc, const Unit& u, int wr, int wc, int fr, int fq) const {
;     ...
;                     } else {
;                         const u32x4 gb = __builtin_nontemporal_load((const u32x4*)(GB + ro + bj * HALF));
;                         r0[0] = bf_lo(ga.x) + bf_lo(gb.x) * a0[0]; r0[1] = bf_hi(ga.x) + bf_hi(gb.x) * a0[1]; r0[2] = bf_lo(ga.y) + bf_lo(gb.y) * a0[2]; r0[3] = bf_hi(ga.y) + bf_hi(gb.y) * a0[3];
;                         r1[0] = bf_lo(ga.z) + bf_lo(gb.z) * a1[0]; r1[1] = bf_hi(ga.z) + bf_hi(gb.z) * a1[1]; r1[2] = bf_lo(ga.w) + bf_lo(gb.w) * a1[2]; r1[3] = bf_hi(ga.w) + bf_hi(gb.w) * a1[3];
;                         *(u32x4*)(GB + ro + bj * HALF) = pack8(r0, r1);
	v_lshlrev_b32_e32 v156, 16, v208
	v_lshlrev_b32_e32 v168, 16, v212
	v_lshlrev_b32_e32 v157, 16, v209
	v_lshlrev_b32_e32 v169, 16, v213
	v_lshlrev_b32_e32 v158, 16, v210
	v_lshlrev_b32_e32 v170, 16, v214
	v_lshlrev_b32_e32 v159, 16, v211
	v_lshlrev_b32_e32 v171, 16, v215
	v_and_b32_e32 v208, 0xffff0000, v208
	v_and_b32_e32 v212, 0xffff0000, v212
	v_and_b32_e32 v209, 0xffff0000, v209
	v_and_b32_e32 v213, 0xffff0000, v213
	v_and_b32_e32 v210, 0xffff0000, v210
	v_and_b32_e32 v214, 0xffff0000, v214
	v_and_b32_e32 v211, 0xffff0000, v211
	v_and_b32_e32 v215, 0xffff0000, v215
	v_fma_f32 v92, v92, v168, v156
	v_fma_f32 v93, v93, v212, v208
	v_fma_f32 v94, v94, v169, v157
	v_fma_f32 v95, v95, v213, v209
	v_fma_f32 v88, v88, v170, v158
	v_fma_f32 v89, v89, v214, v210
	v_fma_f32 v90, v90, v171, v159
	v_fma_f32 v91, v91, v215, v211
	v_cvt_pk_bf16_f32 v92, v92, v93
	v_cvt_pk_bf16_f32 v93, v94, v95
	v_cvt_pk_bf16_f32 v94, v88, v89
	v_cvt_pk_bf16_f32 v95, v90, v91
	v_add_u32_e32 v146, 0x10000, v144
	global_store_dwordx4 v146, v[92:95], s[28:29]
	v_add_u32_e32 v145, 0x48000, v144
	global_load_dwordx4 v[208:211], v145, s[8:9]
	global_load_dwordx4 v[212:215], v145, s[28:29] nt
	s_waitcnt vmcnt(15)
	v_lshlrev_b32_e32 v156, 16, v216
	v_lshlrev_b32_e32 v168, 16, v220
	v_lshlrev_b32_e32 v157, 16, v217
	v_lshlrev_b32_e32 v169, 16, v221
	v_lshlrev_b32_e32 v158, 16, v218
	v_lshlrev_b32_e32 v170, 16, v222
	v_lshlrev_b32_e32 v159, 16, v219
	v_lshlrev_b32_e32 v171, 16, v223
	v_and_b32_e32 v216, 0xffff0000, v216
	v_and_b32_e32 v220, 0xffff0000, v220
	v_and_b32_e32 v217, 0xffff0000, v217
	v_and_b32_e32 v221, 0xffff0000, v221
	v_and_b32_e32 v218, 0xffff0000, v218
	v_and_b32_e32 v222, 0xffff0000, v222
	v_and_b32_e32 v219, 0xffff0000, v219
	v_and_b32_e32 v223, 0xffff0000, v223
	v_fma_f32 v84, v84, v168, v156
	v_fma_f32 v85, v85, v220, v216
	v_fma_f32 v86, v86, v169, v157
	v_fma_f32 v87, v87, v221, v217
	v_fma_f32 v80, v80, v170, v158
	v_fma_f32 v81, v81, v222, v218
	v_fma_f32 v82, v82, v171, v159
	v_fma_f32 v83, v83, v223, v219
	v_cvt_pk_bf16_f32 v84, v84, v85
	v_cvt_pk_bf16_f32 v85, v86, v87
	v_cvt_pk_bf16_f32 v86, v80, v81
	v_cvt_pk_bf16_f32 v87, v82, v83
	global_store_dwordx4 v146, v[84:87], s[28:29] offset:256
	global_load_dwordx4 v[216:219], v145, s[8:9] offset:256
	global_load_dwordx4 v[220:223], v145, s[28:29] offset:256 nt
	s_waitcnt vmcnt(15)
	v_lshlrev_b32_e32 v156, 16, v176
	v_lshlrev_b32_e32 v168, 16, v180
	v_lshlrev_b32_e32 v157, 16, v177
	v_lshlrev_b32_e32 v169, 16, v181
	v_lshlrev_b32_e32 v158, 16, v178
	v_lshlrev_b32_e32 v170, 16, v182
	v_lshlrev_b32_e32 v159, 16, v179
	v_lshlrev_b32_e32 v171, 16, v183
	v_and_b32_e32 v176, 0xffff0000, v176
	v_and_b32_e32 v180, 0xffff0000, v180
	v_and_b32_e32 v177, 0xffff0000, v177
	v_and_b32_e32 v181, 0xffff0000, v181
	v_and_b32_e32 v178, 0xffff0000, v178
	v_and_b32_e32 v182, 0xffff0000, v182
	v_and_b32_e32 v179, 0xffff0000, v179
	v_and_b32_e32 v183, 0xffff0000, v183
	v_fma_f32 v76, v76, v168, v156
	v_fma_f32 v77, v77, v180, v176
	v_fma_f32 v78, v78, v169, v157
	v_fma_f32 v79, v79, v181, v177
	v_fma_f32 v72, v72, v170, v158
	v_fma_f32 v73, v73, v182, v178
	v_fma_f32 v74, v74, v171, v159
	v_fma_f32 v75, v75, v183, v179
	v_cvt_pk_bf16_f32 v76, v76, v77
	v_cvt_pk_bf16_f32 v77, v78, v79
	v_cvt_pk_bf16_f32 v78, v72, v73
	v_cvt_pk_bf16_f32 v79, v74, v75
	v_add_u32_e32 v146, 0x18000, v144
	global_store_dwordx4 v146, v[76:79], s[28:29]
	v_add_u32_e32 v145, 0x50000, v144
	global_load_dwordx4 v[176:179], v145, s[8:9]
	global_load_dwordx4 v[180:183], v145, s[28:29] nt
	s_waitcnt vmcnt(15)
	v_lshlrev_b32_e32 v156, 16, v184
	v_lshlrev_b32_e32 v168, 16, v188
	v_lshlrev_b32_e32 v157, 16, v185
	v_lshlrev_b32_e32 v169, 16, v189
	v_lshlrev_b32_e32 v158, 16, v186
	v_lshlrev_b32_e32 v170, 16, v190
	v_lshlrev_b32_e32 v159, 16, v187
	v_lshlrev_b32_e32 v171, 16, v191
	v_and_b32_e32 v184, 0xffff0000, v184
	v_and_b32_e32 v188, 0xffff0000, v188
	v_and_b32_e32 v185, 0xffff0000, v185
	v_and_b32_e32 v189, 0xffff0000, v189
	v_and_b32_e32 v186, 0xffff0000, v186
	v_and_b32_e32 v190, 0xffff0000, v190
	v_and_b32_e32 v187, 0xffff0000, v187
	v_and_b32_e32 v191, 0xffff0000, v191
	v_fma_f32 v68, v68, v168, v156
	v_fma_f32 v69, v69, v188, v184
	v_fma_f32 v70, v70, v169, v157
	v_fma_f32 v71, v71, v189, v185
	v_fma_f32 v64, v64, v170, v158
	v_fma_f32 v65, v65, v190, v186
	v_fma_f32 v66, v66, v171, v159
	v_fma_f32 v67, v67, v191, v187
	v_cvt_pk_bf16_f32 v68, v68, v69
	v_cvt_pk_bf16_f32 v69, v70, v71
	v_cvt_pk_bf16_f32 v70, v64, v65
	v_cvt_pk_bf16_f32 v71, v66, v67
	global_store_dwordx4 v146, v[68:71], s[28:29] offset:256
	global_load_dwordx4 v[184:187], v145, s[8:9] offset:256
	global_load_dwordx4 v[188:191], v145, s[28:29] offset:256 nt
	s_waitcnt vmcnt(15)
	v_lshlrev_b32_e32 v156, 16, v192
	v_lshlrev_b32_e32 v168, 16, v196
	v_lshlrev_b32_e32 v157, 16, v193
	v_lshlrev_b32_e32 v169, 16, v197
	v_lshlrev_b32_e32 v158, 16, v194
	v_lshlrev_b32_e32 v170, 16, v198
	v_lshlrev_b32_e32 v159, 16, v195
	v_lshlrev_b32_e32 v171, 16, v199
	v_and_b32_e32 v192, 0xffff0000, v192
	v_and_b32_e32 v196, 0xffff0000, v196
	v_and_b32_e32 v193, 0xffff0000, v193
	v_and_b32_e32 v197, 0xffff0000, v197
	v_and_b32_e32 v194, 0xffff0000, v194
	v_and_b32_e32 v198, 0xffff0000, v198
	v_and_b32_e32 v195, 0xffff0000, v195
	v_and_b32_e32 v199, 0xffff0000, v199
	v_fma_f32 v60, v60, v168, v156
	v_fma_f32 v61, v61, v196, v192
	v_fma_f32 v62, v62, v169, v157
	v_fma_f32 v63, v63, v197, v193
	v_fma_f32 v56, v56, v170, v158
	v_fma_f32 v57, v57, v198, v194
	v_fma_f32 v58, v58, v171, v159
	v_fma_f32 v59, v59, v199, v195
	v_cvt_pk_bf16_f32 v60, v60, v61
	v_cvt_pk_bf16_f32 v61, v62, v63
	v_cvt_pk_bf16_f32 v62, v56, v57
	v_cvt_pk_bf16_f32 v63, v58, v59
	v_add_u32_e32 v146, 0x40000, v144
	global_store_dwordx4 v146, v[60:63], s[28:29]
	v_add_u32_e32 v145, 0x58000, v144
	global_load_dwordx4 v[192:195], v145, s[8:9]
	global_load_dwordx4 v[196:199], v145, s[28:29] nt
	s_waitcnt vmcnt(15)
; __device__ __forceinline__ float bf_lo(unsigned w) { return __uint_as_float(w << 16); }
; __device__ __forceinline__ float bf_hi(unsigned w) { return __uint_as_float(w & 0xffff0000u); }
; __device__ __forceinline__ u32x4 pack8(f32x4 a, f32x4 b) { u32x4 w; w.x = cvt_pk_bf16(a[0], a[1]); w.y = cvt_pk_bf16(a[2], a[3]); w.z = cvt_pk_bf16(b[0], b[1]); w.w = cvt_pk_bf16(b[2], b[3]); return w; }
;     __device__ __forceinline__ void operator()(const Acc& acc, const Unit& u, int wr, int wc, int fr, int fq) const {
;     ...
;                     } else {
;                         const u32x4 gb = __builtin_nontemporal_load((const u32x4*)(GB + ro + bj * HALF));
;                         r0[0] = bf_lo(ga.x) + bf_lo(gb.x) * a0[0]; r0[1] = bf_hi(ga.x) + bf_hi(gb.x) * a0[1]; r0[2] = bf_lo(ga.y) + bf_lo(gb.y) * a0[2]; r0[3] = bf_hi(ga.y) + bf_hi(gb.y) * a0[3];
;                         r1[0] = bf_lo(ga.z) + bf_lo(gb.z) * a1[0]; r1[1] = bf_hi(ga.z) + bf_hi(gb.z) * a1[1]; r1[2] = bf_lo(ga.w) + bf_lo(gb.w) * a1[2]; r1[3] = bf_hi(ga.w) + bf_hi(gb.w) * a1[3];
;                         *(u32x4*)(GB + ro + bj * HALF) = pack8(r0, r1);
	v_lshlrev_b32_e32 v156, 16, v200
	v_lshlrev_b32_e32 v168, 16, v204
	v_lshlrev_b32_e32 v157, 16, v201
	v_lshlrev_b32_e32 v169, 16, v205
	v_lshlrev_b32_e32 v158, 16, v202
	v_lshlrev_b32_e32 v170, 16, v206
	v_lshlrev_b32_e32 v159, 16, v203
	v_lshlrev_b32_e32 v171, 16, v207
	v_and_b32_e32 v200, 0xffff0000, v200
	v_and_b32_e32 v204, 0xffff0000, v204
	v_and_b32_e32 v201, 0xffff0000, v201
	v_and_b32_e32 v205, 0xffff0000, v205
	v_and_b32_e32 v202, 0xffff0000, v202
	v_and_b32_e32 v206, 0xffff0000, v206
	v_and_b32_e32 v203, 0xffff0000, v203
	v_and_b32_e32 v207, 0xffff0000, v207
	v_fma_f32 v52, v52, v168, v156
	v_fma_f32 v53, v53, v204, v200
	v_fma_f32 v54, v54, v169, v157
	v_fma_f32 v55, v55, v205, v201
	v_fma_f32 v48, v48, v170, v158
	v_fma_f32 v49, v49, v206, v202
	v_fma_f32 v50, v50, v171, v159
	v_fma_f32 v51, v51, v207, v203
	v_cvt_pk_bf16_f32 v52, v52, v53
	v_cvt_pk_bf16_f32 v53, v54, v55
	v_cvt_pk_bf16_f32 v54, v48, v49
	v_cvt_pk_bf16_f32 v55, v50, v51
	global_store_dwordx4 v146, v[52:55], s[28:29] offset:256
	global_load_dwordx4 v[200:203], v145, s[8:9] offset:256
	global_load_dwordx4 v[204:207], v145, s[28:29] offset:256 nt
	s_waitcnt vmcnt(15)
	v_lshlrev_b32_e32 v156, 16, v208
	v_lshlrev_b32_e32 v168, 16, v212
	v_lshlrev_b32_e32 v157, 16, v209
	v_lshlrev_b32_e32 v169, 16, v213
	v_lshlrev_b32_e32 v158, 16, v210
	v_lshlrev_b32_e32 v170, 16, v214
	v_lshlrev_b32_e32 v159, 16, v211
	v_lshlrev_b32_e32 v171, 16, v215
	v_and_b32_e32 v208, 0xffff0000, v208
	v_and_b32_e32 v212, 0xffff0000, v212
	v_and_b32_e32 v209, 0xffff0000, v209
	v_and_b32_e32 v213, 0xffff0000, v213
	v_and_b32_e32 v210, 0xffff0000, v210
	v_and_b32_e32 v214, 0xffff0000, v214
	v_and_b32_e32 v211, 0xffff0000, v211
	v_and_b32_e32 v215, 0xffff0000, v215
	v_fma_f32 v44, v44, v168, v156
	v_fma_f32 v45, v45, v212, v208
	v_fma_f32 v46, v46, v169, v157
	v_fma_f32 v47, v47, v213, v209
	v_fma_f32 v40, v40, v170, v158
	v_fma_f32 v41, v41, v214, v210
	v_fma_f32 v42, v42, v171, v159
	v_fma_f32 v43, v43, v215, v211
	v_cvt_pk_bf16_f32 v44, v44, v45
	v_cvt_pk_bf16_f32 v45, v46, v47
	v_cvt_pk_bf16_f32 v46, v40, v41
	v_cvt_pk_bf16_f32 v47, v42, v43
	v_add_u32_e32 v146, 0x48000, v144
	global_store_dwordx4 v146, v[44:47], s[28:29]
	s_waitcnt vmcnt(13)
	v_lshlrev_b32_e32 v156, 16, v216
	v_lshlrev_b32_e32 v168, 16, v220
	v_lshlrev_b32_e32 v157, 16, v217
	v_lshlrev_b32_e32 v169, 16, v221
	v_lshlrev_b32_e32 v158, 16, v218
	v_lshlrev_b32_e32 v170, 16, v222
	v_lshlrev_b32_e32 v159, 16, v219
	v_lshlrev_b32_e32 v171, 16, v223
	v_and_b32_e32 v216, 0xffff0000, v216
	v_and_b32_e32 v220, 0xffff0000, v220
	v_and_b32_e32 v217, 0xffff0000, v217
	v_and_b32_e32 v221, 0xffff0000, v221
	v_and_b32_e32 v218, 0xffff0000, v218
	v_and_b32_e32 v222, 0xffff0000, v222
	v_and_b32_e32 v219, 0xffff0000, v219
	v_and_b32_e32 v223, 0xffff0000, v223
	v_fma_f32 v36, v36, v168, v156
	v_fma_f32 v37, v37, v220, v216
	v_fma_f32 v38, v38, v169, v157
	v_fma_f32 v39, v39, v221, v217
	v_fma_f32 v32, v32, v170, v158
	v_fma_f32 v33, v33, v222, v218
	v_fma_f32 v34, v34, v171, v159
	v_fma_f32 v35, v35, v223, v219
	v_cvt_pk_bf16_f32 v36, v36, v37
	v_cvt_pk_bf16_f32 v37, v38, v39
	v_cvt_pk_bf16_f32 v38, v32, v33
	v_cvt_pk_bf16_f32 v39, v34, v35
	global_store_dwordx4 v146, v[36:39], s[28:29] offset:256
	s_waitcnt vmcnt(11)
; __device__ __forceinline__ float bf_lo(unsigned w) { return __uint_as_float(w << 16); }
; __device__ __forceinline__ float bf_hi(unsigned w) { return __uint_as_float(w & 0xffff0000u); }
; __device__ __forceinline__ u32x4 pack8(f32x4 a, f32x4 b) { u32x4 w; w.x = cvt_pk_bf16(a[0], a[1]); w.y = cvt_pk_bf16(a[2], a[3]); w.z = cvt_pk_bf16(b[0], b[1]); w.w = cvt_pk_bf16(b[2], b[3]); return w; }
;     __device__ __forceinline__ void operator()(const Acc& acc, const Unit& u, int wr, int wc, int fr, int fq) const {
;     ...
;                     } else {
;                         const u32x4 gb = __builtin_nontemporal_load((const u32x4*)(GB + ro + bj * HALF));
;                         r0[0] = bf_lo(ga.x) + bf_lo(gb.x) * a0[0]; r0[1] = bf_hi(ga.x) + bf_hi(gb.x) * a0[1]; r0[2] = bf_lo(ga.y) + bf_lo(gb.y) * a0[2]; r0[3] = bf_hi(ga.y) + bf_hi(gb.y) * a0[3];
;                         r1[0] = bf_lo(ga.z) + bf_lo(gb.z) * a1[0]; r1[1] = bf_hi(ga.z) + bf_hi(gb.z) * a1[1]; r1[2] = bf_lo(ga.w) + bf_lo(gb.w) * a1[2]; r1[3] = bf_hi(ga.w) + bf_hi(gb.w) * a1[3];
;                         *(u32x4*)(GB + ro + bj * HALF) = pack8(r0, r1);
	v_lshlrev_b32_e32 v156, 16, v176
	v_lshlrev_b32_e32 v168, 16, v180
	v_lshlrev_b32_e32 v157, 16, v177
	v_lshlrev_b32_e32 v169, 16, v181
	v_lshlrev_b32_e32 v158, 16, v178
	v_lshlrev_b32_e32 v170, 16, v182
	v_lshlrev_b32_e32 v159, 16, v179
	v_lshlrev_b32_e32 v171, 16, v183
	v_and_b32_e32 v176, 0xffff0000, v176
	v_and_b32_e32 v180, 0xffff0000, v180
	v_and_b32_e32 v177, 0xffff0000, v177
	v_and_b32_e32 v181, 0xffff0000, v181
	v_and_b32_e32 v178, 0xffff0000, v178
	v_and_b32_e32 v182, 0xffff0000, v182
	v_and_b32_e32 v179, 0xffff0000, v179
	v_and_b32_e32 v183, 0xffff0000, v183
	v_fma_f32 v28, v28, v168, v156
	v_fma_f32 v29, v29, v180, v176
	v_fma_f32 v30, v30, v169, v157
	v_fma_f32 v31, v31, v181, v177
	v_fma_f32 v24, v24, v170, v158
	v_fma_f32 v25, v25, v182, v178
	v_fma_f32 v26, v26, v171, v159
	v_fma_f32 v27, v27, v183, v179
	v_cvt_pk_bf16_f32 v28, v28, v29
	v_cvt_pk_bf16_f32 v29, v30, v31
	v_cvt_pk_bf16_f32 v30, v24, v25
	v_cvt_pk_bf16_f32 v31, v26, v27
	v_add_u32_e32 v146, 0x50000, v144
	global_store_dwordx4 v146, v[28:31], s[28:29]
	s_waitcnt vmcnt(9)
	v_lshlrev_b32_e32 v156, 16, v184
	v_lshlrev_b32_e32 v168, 16, v188
	v_lshlrev_b32_e32 v157, 16, v185
	v_lshlrev_b32_e32 v169, 16, v189
	v_lshlrev_b32_e32 v158, 16, v186
	v_lshlrev_b32_e32 v170, 16, v190
	v_lshlrev_b32_e32 v159, 16, v187
	v_lshlrev_b32_e32 v171, 16, v191
	v_and_b32_e32 v184, 0xffff0000, v184
	v_and_b32_e32 v188, 0xffff0000, v188
	v_and_b32_e32 v185, 0xffff0000, v185
	v_and_b32_e32 v189, 0xffff0000, v189
	v_and_b32_e32 v186, 0xffff0000, v186
	v_and_b32_e32 v190, 0xffff0000, v190
	v_and_b32_e32 v187, 0xffff0000, v187
	v_and_b32_e32 v191, 0xffff0000, v191
	v_fma_f32 v20, v20, v168, v156
	v_fma_f32 v21, v21, v188, v184
	v_fma_f32 v22, v22, v169, v157
	v_fma_f32 v23, v23, v189, v185
	v_fma_f32 v16, v16, v170, v158
	v_fma_f32 v17, v17, v190, v186
	v_fma_f32 v18, v18, v171, v159
	v_fma_f32 v19, v19, v191, v187
	v_cvt_pk_bf16_f32 v20, v20, v21
	v_cvt_pk_bf16_f32 v21, v22, v23
	v_cvt_pk_bf16_f32 v22, v16, v17
	v_cvt_pk_bf16_f32 v23, v18, v19
	global_store_dwordx4 v146, v[20:23], s[28:29] offset:256
	s_waitcnt vmcnt(7)
	v_lshlrev_b32_e32 v156, 16, v192
	v_lshlrev_b32_e32 v168, 16, v196
	v_lshlrev_b32_e32 v157, 16, v193
	v_lshlrev_b32_e32 v169, 16, v197
	v_lshlrev_b32_e32 v158, 16, v194
	v_lshlrev_b32_e32 v170, 16, v198
	v_lshlrev_b32_e32 v159, 16, v195
	v_lshlrev_b32_e32 v171, 16, v199
	v_and_b32_e32 v192, 0xffff0000, v192
	v_and_b32_e32 v196, 0xffff0000, v196
	v_and_b32_e32 v193, 0xffff0000, v193
	v_and_b32_e32 v197, 0xffff0000, v197
	v_and_b32_e32 v194, 0xffff0000, v194
	v_and_b32_e32 v198, 0xffff0000, v198
	v_and_b32_e32 v195, 0xffff0000, v195
	v_and_b32_e32 v199, 0xffff0000, v199
	v_fma_f32 v12, v12, v168, v156
	v_fma_f32 v13, v13, v196, v192
	v_fma_f32 v14, v14, v169, v157
	v_fma_f32 v15, v15, v197, v193
	v_fma_f32 v8, v8, v170, v158
	v_fma_f32 v9, v9, v198, v194
	v_fma_f32 v10, v10, v171, v159
	v_fma_f32 v11, v11, v199, v195
	v_cvt_pk_bf16_f32 v12, v12, v13
	v_cvt_pk_bf16_f32 v13, v14, v15
	v_cvt_pk_bf16_f32 v14, v8, v9
	v_cvt_pk_bf16_f32 v15, v10, v11
	v_add_u32_e32 v146, 0x58000, v144
	global_store_dwordx4 v146, v[12:15], s[28:29]
	s_waitcnt vmcnt(5)
	v_lshlrev_b32_e32 v156, 16, v200
	v_lshlrev_b32_e32 v168, 16, v204
	v_lshlrev_b32_e32 v157, 16, v201
	v_lshlrev_b32_e32 v169, 16, v205
	v_lshlrev_b32_e32 v158, 16, v202
	v_lshlrev_b32_e32 v170, 16, v206
	v_lshlrev_b32_e32 v159, 16, v203
	v_lshlrev_b32_e32 v171, 16, v207
	v_and_b32_e32 v200, 0xffff0000, v200
	v_and_b32_e32 v204, 0xffff0000, v204
	v_and_b32_e32 v201, 0xffff0000, v201
	v_and_b32_e32 v205, 0xffff0000, v205
	v_and_b32_e32 v202, 0xffff0000, v202
	v_and_b32_e32 v206, 0xffff0000, v206
	v_and_b32_e32 v203, 0xffff0000, v203
	v_and_b32_e32 v207, 0xffff0000, v207
	v_fma_f32 v4, v4, v168, v156
	v_fma_f32 v5, v5, v204, v200
	v_fma_f32 v6, v6, v169, v157
	v_fma_f32 v7, v7, v205, v201
	v_fma_f32 v0, v0, v170, v158
	v_fma_f32 v1, v1, v206, v202
	v_fma_f32 v2, v2, v171, v159
	v_fma_f32 v3, v3, v207, v203
	v_cvt_pk_bf16_f32 v4, v4, v5
	v_cvt_pk_bf16_f32 v5, v6, v7
	v_cvt_pk_bf16_f32 v6, v0, v1
	v_cvt_pk_bf16_f32 v7, v2, v3
	global_store_dwordx4 v146, v[4:7], s[28:29] offset:256
	s_cbranch_vccnz .LBB0_1029
	s_andn2_b64 vcc, exec, s[10:11]
	s_cbranch_vccnz .LBB0_1028
	s_barrier
	s_branch .LBB0_1028
